# gMLP mixer: token-half template alternates per item (wave parity xor item-counter bit 7) so each wave gets one short and one long item; on top of the batched census loads
# baseline (speedup 1.0000x reference)
.LBB0_480:
	s_and_b64 vcc, exec, s[0:1]
	s_cbranch_vccz .LBB0_467
	s_lshr_b32 s17, s8, 4
	s_bfe_u32 s20, s23, 0x30001
	s_mul_i32 s0, s17, 0x160000
	s_add_u32 s8, s19, s0
	s_addc_u32 s11, s25, 0
	s_lshl_b32 s16, s20, 6
	s_lshl_b32 s0, s20, 7
	s_add_u32 s0, s8, s0
	s_addc_u32 s1, s11, 0
	v_lshl_add_u64 v[88:89], s[0:1], 0, v[74:75]
	v_add_co_u32_e32 v94, vcc, s81, v88
	s_mov_b32 s0, 0x2c000
	s_nop 0
	v_addc_co_u32_e32 v95, vcc, 0, v89, vcc
	v_add_co_u32_e32 v92, vcc, s0, v88
	s_mov_b32 s0, 0x58000
	s_nop 0
	v_addc_co_u32_e32 v93, vcc, 0, v89, vcc
	v_add_co_u32_e32 v14, vcc, 0x42000, v88
	global_load_dwordx4 v[2:5], v[88:89], off offset:3072
	s_nop 0
	v_addc_co_u32_e32 v15, vcc, 0, v89, vcc
	v_add_co_u32_e32 v90, vcc, s0, v88
	global_load_dwordx4 v[6:9], v[94:95], off offset:3072
	global_load_dwordx4 v[10:13], v[92:93], off offset:3072
	v_addc_co_u32_e32 v91, vcc, 0, v89, vcc
	v_add_co_u32_e32 v22, vcc, 0x6e000, v88
	global_load_dwordx4 v[14:17], v[14:15], off offset:3072
	s_nop 0
	v_addc_co_u32_e32 v23, vcc, 0, v89, vcc
	v_add_co_u32_e32 v28, vcc, 0x84000, v88
	global_load_dwordx4 v[18:21], v[90:91], off offset:3072
	s_nop 0
	v_addc_co_u32_e32 v29, vcc, 0, v89, vcc
	v_add_co_u32_e32 v32, vcc, 0x9a000, v88
	global_load_dwordx4 v[22:25], v[22:23], off offset:3072
	s_nop 0
	v_addc_co_u32_e32 v33, vcc, 0, v89, vcc
	global_load_dwordx4 v[28:31], v[28:29], off offset:3072
	v_readlane_b32 s4, v251, 43
	global_load_dwordx4 v[32:35], v[32:33], off offset:3072
	v_readlane_b32 s5, v251, 44
	s_bitcmp1_b32 s23, 7
	s_cselect_b64 s[98:99], -1, 0
	s_xor_b64 s[4:5], s[4:5], s[98:99]
	s_mov_b64 s[0:1], -1
	v_add_u32_e32 v162, 0x880, v135
	v_add_u32_e32 v154, 0xcc0, v135
	s_andn2_b64 vcc, exec, s[4:5]
	v_add_u32_e32 v147, 0x1100, v135
	v_add_u32_e32 v138, 0x1540, v135
	v_add_u32_e32 v107, 0x1980, v135
	v_add_u32_e32 v98, 0x1dc0, v135
	s_waitcnt vmcnt(7)
	v_lshlrev_b32_e32 v197, 16, v2
	v_and_b32_e32 v196, 0xffff0000, v2
	v_lshlrev_b32_e32 v195, 16, v3
	v_and_b32_e32 v194, 0xffff0000, v3
	v_lshlrev_b32_e32 v193, 16, v4
	v_and_b32_e32 v192, 0xffff0000, v4
	v_lshlrev_b32_e32 v191, 16, v5
	v_and_b32_e32 v190, 0xffff0000, v5
	s_waitcnt vmcnt(6)
	v_lshlrev_b32_e32 v189, 16, v6
	v_and_b32_e32 v188, 0xffff0000, v6
	v_lshlrev_b32_e32 v187, 16, v7
	v_and_b32_e32 v186, 0xffff0000, v7
	v_lshlrev_b32_e32 v185, 16, v8
	v_and_b32_e32 v184, 0xffff0000, v8
	v_lshlrev_b32_e32 v183, 16, v9
	v_and_b32_e32 v182, 0xffff0000, v9
	s_waitcnt vmcnt(5)
	v_lshlrev_b32_e32 v181, 16, v10
	v_and_b32_e32 v180, 0xffff0000, v10
	v_lshlrev_b32_e32 v179, 16, v11
	v_and_b32_e32 v178, 0xffff0000, v11
	v_lshlrev_b32_e32 v177, 16, v12
	v_and_b32_e32 v176, 0xffff0000, v12
	v_lshlrev_b32_e32 v167, 16, v13
	v_and_b32_e32 v166, 0xffff0000, v13
	s_waitcnt vmcnt(4)
	v_lshlrev_b32_e32 v165, 16, v14
	v_and_b32_e32 v164, 0xffff0000, v14
	v_lshlrev_b32_e32 v163, 16, v15
	v_and_b32_e32 v161, 0xffff0000, v15
	v_lshlrev_b32_e32 v160, 16, v16
	v_and_b32_e32 v159, 0xffff0000, v16
	v_lshlrev_b32_e32 v158, 16, v17
	v_and_b32_e32 v157, 0xffff0000, v17
	s_waitcnt vmcnt(3)
	v_lshlrev_b32_e32 v156, 16, v18
	v_and_b32_e32 v155, 0xffff0000, v18
	v_lshlrev_b32_e32 v153, 16, v19
	v_and_b32_e32 v152, 0xffff0000, v19
	v_lshlrev_b32_e32 v151, 16, v20
	v_and_b32_e32 v150, 0xffff0000, v20
	v_lshlrev_b32_e32 v149, 16, v21
	v_and_b32_e32 v148, 0xffff0000, v21
	s_waitcnt vmcnt(2)
	v_lshlrev_b32_e32 v146, 16, v22
	v_and_b32_e32 v145, 0xffff0000, v22
	v_lshlrev_b32_e32 v144, 16, v23
	v_and_b32_e32 v143, 0xffff0000, v23
	v_lshlrev_b32_e32 v142, 16, v24
	v_and_b32_e32 v141, 0xffff0000, v24
	v_lshlrev_b32_e32 v140, 16, v25
	v_and_b32_e32 v139, 0xffff0000, v25
	s_waitcnt vmcnt(1)
	v_lshlrev_b32_e32 v137, 16, v28
	v_and_b32_e32 v136, 0xffff0000, v28
	v_lshlrev_b32_e32 v113, 16, v29
	v_and_b32_e32 v112, 0xffff0000, v29
	v_lshlrev_b32_e32 v111, 16, v30
	v_and_b32_e32 v110, 0xffff0000, v30
	v_lshlrev_b32_e32 v109, 16, v31
	v_and_b32_e32 v108, 0xffff0000, v31
	s_waitcnt vmcnt(0)
	v_lshlrev_b32_e32 v106, 16, v32
	v_and_b32_e32 v105, 0xffff0000, v32
	v_lshlrev_b32_e32 v104, 16, v33
	v_and_b32_e32 v103, 0xffff0000, v33
	v_lshlrev_b32_e32 v102, 16, v34
	v_and_b32_e32 v101, 0xffff0000, v34
	v_lshlrev_b32_e32 v100, 16, v35
	v_and_b32_e32 v99, 0xffff0000, v35
	s_cbranch_vccnz .LBB0_485
	v_lshl_add_u64 v[2:3], v[88:89], 0, s[86:87]
	v_add_co_u32_e32 v4, vcc, 0xb0000, v2
	s_lshl_b32 s0, s23, 14
	s_nop 0
	v_addc_co_u32_e32 v5, vcc, 0, v3, vcc
	global_load_dwordx4 v[52:55], v[4:5], off
	v_add_co_u32_e32 v4, vcc, 0xc6000, v2
	s_and_b32 s68, s0, 0x38000
	s_nop 0
	v_addc_co_u32_e32 v5, vcc, 0, v3, vcc
	global_load_dwordx4 v[48:51], v[4:5], off
	v_add_co_u32_e32 v4, vcc, 0xdc000, v2
	v_lshl_add_u64 v[96:97], v[86:87], 0, s[68:69]
	s_nop 0
	v_addc_co_u32_e32 v5, vcc, 0, v3, vcc
	global_load_dwordx4 v[44:47], v[4:5], off
	v_add_co_u32_e32 v4, vcc, 0xf2000, v2
	s_lshl_b32 s68, s17, 13
	s_nop 0
	v_addc_co_u32_e32 v5, vcc, 0, v3, vcc
	global_load_dwordx4 v[36:39], v[4:5], off
	v_add_co_u32_e32 v4, vcc, 0x108000, v2
	s_mov_b64 s[4:5], 0x1000
	s_nop 0
	v_addc_co_u32_e32 v5, vcc, 0, v3, vcc
	global_load_dwordx4 v[16:19], v[4:5], off
	v_add_co_u32_e32 v4, vcc, 0x11e000, v2
	s_mov_b32 s1, 0x3b000000
	s_nop 0
	v_addc_co_u32_e32 v5, vcc, 0, v3, vcc
	global_load_dwordx4 v[12:15], v[4:5], off
	v_add_co_u32_e32 v4, vcc, 0x134000, v2
	s_mov_b32 s0, 0
	s_nop 0
	v_addc_co_u32_e32 v5, vcc, 0, v3, vcc
	v_add_co_u32_e32 v2, vcc, 0x14a000, v2
	global_load_dwordx4 v[8:11], v[4:5], off
	s_nop 0
	v_addc_co_u32_e32 v3, vcc, 0, v3, vcc
	global_load_dwordx4 v[4:7], v[2:3], off
	v_lshl_add_u64 v[2:3], v[76:77], 0, s[68:69]
	global_load_dwordx4 v[56:59], v[2:3], off offset:48
	global_load_dwordx4 v[60:63], v[2:3], off offset:32
	global_load_dwordx4 v[64:67], v[2:3], off offset:16
	global_load_dwordx4 v[198:201], v[2:3], off
	v_lshl_add_u64 v[20:21], v[2:3], 0, s[4:5]
	v_add_co_u32_e32 v2, vcc, s10, v2
	s_lshl_b32 s68, s16, 2
	s_nop 0
	v_addc_co_u32_e32 v3, vcc, 0, v3, vcc
	global_load_dwordx4 v[202:205], v[2:3], off
	global_load_dwordx4 v[206:209], v[20:21], off offset:48
	global_load_dwordx4 v[210:213], v[20:21], off offset:32
	global_load_dwordx4 v[214:217], v[20:21], off offset:16
	v_lshl_add_u64 v[2:3], v[82:83], 0, s[68:69]
	global_load_dwordx4 v[20:23], v[2:3], off offset:16
	global_load_dwordx4 v[32:35], v[2:3], off
	v_lshl_add_u64 v[2:3], v[84:85], 0, s[68:69]
	global_load_dwordx4 v[28:31], v[2:3], off offset:16
	global_load_dwordx4 v[40:43], v[2:3], off
	s_waitcnt vmcnt(11)
	v_mov_b32_e32 v25, v58
	s_waitcnt vmcnt(10)
	v_mov_b32_e32 v24, v62
	s_waitcnt vmcnt(9)
	v_add_f32_e32 v3, v64, v66
	s_waitcnt vmcnt(8)
	v_add_f32_e32 v2, v198, v200
	v_add_f32_e32 v64, v2, v3
	v_mov_b32_e32 v2, v60
	v_mov_b32_e32 v3, v56
	v_pk_add_f32 v[2:3], v[2:3], v[24:25]
	v_add_f32_e32 v24, v65, v67
	v_add_f32_e32 v2, v64, v2
	v_add_f32_e32 v2, v2, v3
	v_add_f32_e32 v3, v199, v201
	v_add_f32_e32 v3, v3, v24
	v_add_f32_e32 v24, v61, v63
	v_add_f32_e32 v3, v3, v24
	v_add_f32_e32 v24, v57, v59
	v_mul_f32_e32 v60, 0x3b000000, v2
	v_add_f32_e32 v3, v3, v24
	v_mul_f32_e32 v2, v60, v60
	v_fma_f32 v3, v3, s1, -v2
	v_max_f32_e32 v3, 0, v3
	v_add_f32_e32 v3, 0x3727c5ac, v3
	v_rsq_f32_e32 v61, v3
	s_waitcnt vmcnt(7)
	v_add_f32_e32 v3, v202, v204
	s_waitcnt vmcnt(4)
	v_add_f32_e32 v24, v214, v216
	v_add_f32_e32 v3, v3, v24
	v_mov_b32_e32 v24, v210
	v_mov_b32_e32 v25, v206
	v_mov_b32_e32 v56, v212
	v_mov_b32_e32 v57, v208
	v_pk_add_f32 v[24:25], v[24:25], v[56:57]
	v_mov_b32_e32 v2, 0
	v_add_f32_e32 v3, v3, v24
	v_add_f32_e32 v3, v3, v25
	v_add_f32_e32 v24, v203, v205
	v_add_f32_e32 v25, v215, v217
	v_add_f32_e32 v24, v24, v25
	v_add_f32_e32 v25, v211, v213
	v_add_f32_e32 v24, v24, v25
	v_add_f32_e32 v25, v207, v209
	v_mul_f32_e32 v3, 0x3b000000, v3
	v_add_f32_e32 v24, v24, v25
	v_mul_f32_e32 v25, v3, v3
	v_fma_f32 v24, v24, s1, -v25
	v_and_b32_e32 v25, 64, v224
	v_or_b32_e32 v56, v25, v114
	v_lshlrev_b32_e32 v62, 2, v56
	ds_bpermute_b32 v59, v62, v60
	ds_bpermute_b32 v63, v62, v61
	v_max_f32_e32 v24, 0, v24
	v_add_f32_e32 v24, 0x3727c5ac, v24
	v_rsq_f32_e32 v24, v24
	s_waitcnt lgkmcnt(1)
	v_sub_f32_e32 v56, v197, v59
	v_sub_f32_e32 v57, v196, v59
	s_waitcnt lgkmcnt(0)
	v_mul_f32_e32 v56, v56, v63
	v_mul_f32_e32 v57, v57, v63
	s_waitcnt vmcnt(0)
	v_fma_f32 v56, v32, v56, v40
	v_fma_f32 v57, v33, v57, v41
	v_cvt_pk_bf16_f32 v56, v56, v57
	v_sub_f32_e32 v57, v195, v59
	v_sub_f32_e32 v58, v194, v59
	v_mul_f32_e32 v57, v57, v63
	v_mul_f32_e32 v58, v58, v63
	v_fma_f32 v57, v34, v57, v42
	v_fma_f32 v58, v35, v58, v43
	v_cvt_pk_bf16_f32 v57, v57, v58
	v_sub_f32_e32 v58, v193, v59
	v_sub_f32_e32 v64, v192, v59
	v_mul_f32_e32 v58, v58, v63
	v_mul_f32_e32 v64, v64, v63
	v_fma_f32 v58, v20, v58, v28
	v_fma_f32 v64, v21, v64, v29
	v_cvt_pk_bf16_f32 v58, v58, v64
	v_sub_f32_e32 v64, v191, v59
	v_sub_f32_e32 v59, v190, v59
	v_mul_f32_e32 v59, v59, v63
	v_mul_f32_e32 v64, v64, v63
	v_fma_f32 v59, v23, v59, v31
	v_fma_f32 v64, v22, v64, v30
	v_cvt_pk_bf16_f32 v59, v64, v59
	ds_write2_b64 v135, v[56:57], v[58:59] offset1:1
	v_or_b32_e32 v56, v25, v115
	v_lshlrev_b32_e32 v56, 2, v56
	ds_bpermute_b32 v59, v56, v60
	ds_bpermute_b32 v63, v56, v61
	v_mov_b32_e32 v65, v2
	v_mov_b32_e32 v66, v2
	v_mov_b32_e32 v67, v2
	s_waitcnt lgkmcnt(1)
	v_sub_f32_e32 v56, v189, v59
	v_sub_f32_e32 v57, v188, v59
	s_waitcnt lgkmcnt(0)
	v_mul_f32_e32 v56, v56, v63
	v_mul_f32_e32 v57, v57, v63
	v_fma_f32 v56, v32, v56, v40
	v_fma_f32 v57, v33, v57, v41
	v_cvt_pk_bf16_f32 v56, v56, v57
	v_sub_f32_e32 v57, v187, v59
	v_sub_f32_e32 v58, v186, v59
	v_mul_f32_e32 v57, v57, v63
	v_mul_f32_e32 v58, v58, v63
	v_fma_f32 v57, v34, v57, v42
	v_fma_f32 v58, v35, v58, v43
	v_cvt_pk_bf16_f32 v57, v57, v58
	v_sub_f32_e32 v58, v185, v59
	v_sub_f32_e32 v64, v184, v59
	v_mul_f32_e32 v58, v58, v63
	v_mul_f32_e32 v64, v64, v63
	v_fma_f32 v58, v20, v58, v28
	v_fma_f32 v64, v21, v64, v29
	v_cvt_pk_bf16_f32 v58, v58, v64
	v_sub_f32_e32 v64, v183, v59
	v_sub_f32_e32 v59, v182, v59
	v_mul_f32_e32 v59, v59, v63
	v_mul_f32_e32 v64, v64, v63
	v_fma_f32 v59, v23, v59, v31
	v_fma_f32 v64, v22, v64, v30
	v_cvt_pk_bf16_f32 v59, v64, v59
	ds_write2_b64 v135, v[56:57], v[58:59] offset0:136 offset1:137
	v_or_b32_e32 v56, v25, v116
	v_lshlrev_b32_e32 v56, 2, v56
	ds_bpermute_b32 v59, v56, v60
	ds_bpermute_b32 v63, v56, v61
	s_waitcnt lgkmcnt(1)
	v_sub_f32_e32 v56, v181, v59
	v_sub_f32_e32 v57, v180, v59
	s_waitcnt lgkmcnt(0)
	v_mul_f32_e32 v56, v56, v63
	v_mul_f32_e32 v57, v57, v63
	v_fma_f32 v56, v32, v56, v40
	v_fma_f32 v57, v33, v57, v41
	v_cvt_pk_bf16_f32 v56, v56, v57
	v_sub_f32_e32 v57, v179, v59
	v_sub_f32_e32 v58, v178, v59
	v_mul_f32_e32 v57, v57, v63
	v_mul_f32_e32 v58, v58, v63
	v_fma_f32 v57, v34, v57, v42
	v_fma_f32 v58, v35, v58, v43
	v_cvt_pk_bf16_f32 v57, v57, v58
	v_sub_f32_e32 v58, v177, v59
	v_sub_f32_e32 v64, v176, v59
	v_mul_f32_e32 v58, v58, v63
	v_mul_f32_e32 v64, v64, v63
	v_fma_f32 v58, v20, v58, v28
	v_fma_f32 v64, v21, v64, v29
	v_cvt_pk_bf16_f32 v58, v58, v64
	v_sub_f32_e32 v64, v167, v59
	v_sub_f32_e32 v59, v166, v59
	v_mul_f32_e32 v59, v59, v63
	v_mul_f32_e32 v64, v64, v63
	v_fma_f32 v59, v23, v59, v31
	v_fma_f32 v64, v22, v64, v30
	v_cvt_pk_bf16_f32 v59, v64, v59
	ds_write2_b64 v162, v[56:57], v[58:59] offset1:1
	v_or_b32_e32 v56, v25, v117
	v_lshlrev_b32_e32 v56, 2, v56
	ds_bpermute_b32 v59, v56, v60
	ds_bpermute_b32 v63, v56, v61
	s_waitcnt lgkmcnt(1)
	v_sub_f32_e32 v56, v165, v59
	v_sub_f32_e32 v57, v164, v59
	s_waitcnt lgkmcnt(0)
	v_mul_f32_e32 v56, v56, v63
	v_mul_f32_e32 v57, v57, v63
	v_fma_f32 v56, v32, v56, v40
	v_fma_f32 v57, v33, v57, v41
	v_cvt_pk_bf16_f32 v56, v56, v57
	v_sub_f32_e32 v57, v163, v59
	v_sub_f32_e32 v58, v161, v59
	v_mul_f32_e32 v57, v57, v63
	v_mul_f32_e32 v58, v58, v63
	v_fma_f32 v57, v34, v57, v42
	v_fma_f32 v58, v35, v58, v43
	v_cvt_pk_bf16_f32 v57, v57, v58
	v_sub_f32_e32 v58, v160, v59
	v_sub_f32_e32 v64, v159, v59
	v_mul_f32_e32 v58, v58, v63
	v_mul_f32_e32 v64, v64, v63
	v_fma_f32 v58, v20, v58, v28
	v_fma_f32 v64, v21, v64, v29
	v_cvt_pk_bf16_f32 v58, v58, v64
	v_sub_f32_e32 v64, v158, v59
	v_sub_f32_e32 v59, v157, v59
	v_mul_f32_e32 v59, v59, v63
	v_mul_f32_e32 v64, v64, v63
	v_fma_f32 v59, v23, v59, v31
	v_fma_f32 v64, v22, v64, v30
	v_cvt_pk_bf16_f32 v59, v64, v59
	ds_write2_b64 v154, v[56:57], v[58:59] offset1:1
	v_or_b32_e32 v56, v25, v118
	v_lshlrev_b32_e32 v56, 2, v56
	ds_bpermute_b32 v59, v56, v60
	ds_bpermute_b32 v63, v56, v61
	s_waitcnt lgkmcnt(1)
	v_sub_f32_e32 v56, v156, v59
	v_sub_f32_e32 v57, v155, v59
	s_waitcnt lgkmcnt(0)
	v_mul_f32_e32 v56, v56, v63
	v_mul_f32_e32 v57, v57, v63
	v_fma_f32 v56, v32, v56, v40
	v_fma_f32 v57, v33, v57, v41
	v_cvt_pk_bf16_f32 v56, v56, v57
	v_sub_f32_e32 v57, v153, v59
	v_sub_f32_e32 v58, v152, v59
	v_mul_f32_e32 v57, v57, v63
	v_mul_f32_e32 v58, v58, v63
	v_fma_f32 v57, v34, v57, v42
	v_fma_f32 v58, v35, v58, v43
	v_cvt_pk_bf16_f32 v57, v57, v58
	v_sub_f32_e32 v58, v151, v59
	v_sub_f32_e32 v64, v150, v59
	v_mul_f32_e32 v58, v58, v63
	v_mul_f32_e32 v64, v64, v63
	v_fma_f32 v58, v20, v58, v28
	v_fma_f32 v64, v21, v64, v29
	v_cvt_pk_bf16_f32 v58, v58, v64
	v_sub_f32_e32 v64, v149, v59
	v_sub_f32_e32 v59, v148, v59
	v_mul_f32_e32 v59, v59, v63
	v_mul_f32_e32 v64, v64, v63
	v_fma_f32 v59, v23, v59, v31
	v_fma_f32 v64, v22, v64, v30
	v_cvt_pk_bf16_f32 v59, v64, v59
	ds_write2_b64 v147, v[56:57], v[58:59] offset1:1
	v_or_b32_e32 v56, v25, v119
	v_lshlrev_b32_e32 v56, 2, v56
	ds_bpermute_b32 v59, v56, v60
	ds_bpermute_b32 v63, v56, v61
	s_waitcnt lgkmcnt(1)
	v_sub_f32_e32 v56, v146, v59
	v_sub_f32_e32 v57, v145, v59
	s_waitcnt lgkmcnt(0)
	v_mul_f32_e32 v56, v56, v63
	v_mul_f32_e32 v57, v57, v63
	v_fma_f32 v56, v32, v56, v40
	v_fma_f32 v57, v33, v57, v41
	v_cvt_pk_bf16_f32 v56, v56, v57
	v_sub_f32_e32 v57, v144, v59
	v_sub_f32_e32 v58, v143, v59
	v_mul_f32_e32 v57, v57, v63
	v_mul_f32_e32 v58, v58, v63
	v_fma_f32 v57, v34, v57, v42
	v_fma_f32 v58, v35, v58, v43
	v_cvt_pk_bf16_f32 v57, v57, v58
	v_sub_f32_e32 v58, v142, v59
	v_sub_f32_e32 v64, v141, v59
	v_mul_f32_e32 v58, v58, v63
	v_mul_f32_e32 v64, v64, v63
	v_fma_f32 v58, v20, v58, v28
	v_fma_f32 v64, v21, v64, v29
	v_cvt_pk_bf16_f32 v58, v58, v64
	v_sub_f32_e32 v64, v140, v59
	v_sub_f32_e32 v59, v139, v59
	v_mul_f32_e32 v59, v59, v63
	v_mul_f32_e32 v64, v64, v63
	v_fma_f32 v59, v23, v59, v31
	v_fma_f32 v64, v22, v64, v30
	v_cvt_pk_bf16_f32 v59, v64, v59
	ds_write2_b64 v138, v[56:57], v[58:59] offset1:1
	v_or_b32_e32 v56, v25, v120
	v_lshlrev_b32_e32 v56, 2, v56
	ds_bpermute_b32 v59, v56, v60
	ds_bpermute_b32 v63, v56, v61
	s_waitcnt lgkmcnt(1)
	v_sub_f32_e32 v56, v137, v59
	v_sub_f32_e32 v57, v136, v59
	s_waitcnt lgkmcnt(0)
	v_mul_f32_e32 v56, v56, v63
	v_mul_f32_e32 v57, v57, v63
	v_fma_f32 v56, v32, v56, v40
	v_fma_f32 v57, v33, v57, v41
	v_cvt_pk_bf16_f32 v56, v56, v57
	v_sub_f32_e32 v57, v113, v59
	v_sub_f32_e32 v58, v112, v59
	v_mul_f32_e32 v57, v57, v63
	v_mul_f32_e32 v58, v58, v63
	v_fma_f32 v57, v34, v57, v42
	v_fma_f32 v58, v35, v58, v43
	v_cvt_pk_bf16_f32 v57, v57, v58
	v_sub_f32_e32 v58, v111, v59
	v_sub_f32_e32 v64, v110, v59
	v_mul_f32_e32 v58, v58, v63
	v_mul_f32_e32 v64, v64, v63
	v_fma_f32 v58, v20, v58, v28
	v_fma_f32 v64, v21, v64, v29
	v_cvt_pk_bf16_f32 v58, v58, v64
	v_sub_f32_e32 v64, v109, v59
	v_sub_f32_e32 v59, v108, v59
	v_mul_f32_e32 v59, v59, v63
	v_mul_f32_e32 v64, v64, v63
	v_fma_f32 v59, v23, v59, v31
	v_fma_f32 v64, v22, v64, v30
	v_cvt_pk_bf16_f32 v59, v64, v59
	ds_write2_b64 v107, v[56:57], v[58:59] offset1:1
	v_or_b32_e32 v56, v25, v121
	v_lshlrev_b32_e32 v56, 2, v56
	ds_bpermute_b32 v59, v56, v60
	ds_bpermute_b32 v60, v56, v61
	v_mov_b32_e32 v63, v2
	v_mov_b32_e32 v64, v2
	s_waitcnt lgkmcnt(1)
	v_sub_f32_e32 v56, v106, v59
	v_sub_f32_e32 v57, v105, v59
	s_waitcnt lgkmcnt(0)
	v_mul_f32_e32 v56, v56, v60
	v_mul_f32_e32 v57, v57, v60
	v_fma_f32 v56, v32, v56, v40
	v_fma_f32 v57, v33, v57, v41
	v_cvt_pk_bf16_f32 v56, v56, v57
	v_sub_f32_e32 v57, v104, v59
	v_sub_f32_e32 v58, v103, v59
	v_mul_f32_e32 v57, v57, v60
	v_mul_f32_e32 v58, v58, v60
	v_fma_f32 v57, v34, v57, v42
	v_fma_f32 v58, v35, v58, v43
	v_cvt_pk_bf16_f32 v57, v57, v58
	v_sub_f32_e32 v58, v102, v59
	v_sub_f32_e32 v61, v101, v59
	v_mul_f32_e32 v58, v58, v60
	v_mul_f32_e32 v61, v61, v60
	v_fma_f32 v58, v20, v58, v28
	v_fma_f32 v61, v21, v61, v29
	v_cvt_pk_bf16_f32 v58, v58, v61
	v_sub_f32_e32 v61, v100, v59
	v_sub_f32_e32 v59, v99, v59
	v_mul_f32_e32 v59, v59, v60
	v_mul_f32_e32 v61, v61, v60
	v_fma_f32 v59, v23, v59, v31
	v_fma_f32 v61, v22, v61, v30
	v_cvt_pk_bf16_f32 v59, v61, v59
	ds_write2_b64 v98, v[56:57], v[58:59] offset1:1
	ds_bpermute_b32 v56, v62, v3
	ds_bpermute_b32 v57, v62, v24
	v_lshlrev_b32_e32 v58, 16, v52
	v_and_b32_e32 v52, 0xffff0000, v52
	v_mov_b32_e32 v59, v2
	s_waitcnt lgkmcnt(1)
	v_sub_f32_e32 v58, v58, v56
	v_sub_f32_e32 v52, v52, v56
	s_waitcnt lgkmcnt(0)
	v_mul_f32_e32 v58, v58, v57
	v_mul_f32_e32 v52, v52, v57
	v_fma_f32 v58, v32, v58, v40
	v_fma_f32 v52, v33, v52, v41
	v_cvt_pk_bf16_f32 v52, v58, v52
	v_lshlrev_b32_e32 v58, 16, v53
	v_and_b32_e32 v53, 0xffff0000, v53
	v_sub_f32_e32 v58, v58, v56
	v_sub_f32_e32 v53, v53, v56
	v_mul_f32_e32 v58, v58, v57
	v_mul_f32_e32 v53, v53, v57
	v_fma_f32 v58, v34, v58, v42
	v_fma_f32 v53, v35, v53, v43
	v_cvt_pk_bf16_f32 v53, v58, v53
	v_lshlrev_b32_e32 v58, 16, v54
	v_and_b32_e32 v54, 0xffff0000, v54
	v_sub_f32_e32 v58, v58, v56
	v_sub_f32_e32 v54, v54, v56
	v_mul_f32_e32 v58, v58, v57
	v_mul_f32_e32 v54, v54, v57
	v_fma_f32 v58, v20, v58, v28
	v_fma_f32 v54, v21, v54, v29
	v_cvt_pk_bf16_f32 v54, v58, v54
	v_lshlrev_b32_e32 v58, 16, v55
	v_and_b32_e32 v55, 0xffff0000, v55
	v_sub_f32_e32 v55, v55, v56
	v_sub_f32_e32 v58, v58, v56
	v_mul_f32_e32 v55, v55, v57
	v_mul_f32_e32 v58, v58, v57
	v_fma_f32 v55, v23, v55, v31
	v_add_u32_e32 v56, 0x2200, v135
	v_fma_f32 v58, v22, v58, v30
	v_cvt_pk_bf16_f32 v55, v58, v55
	ds_write2_b64 v56, v[52:53], v[54:55] offset1:1
	v_or_b32_e32 v52, v25, v122
	v_lshlrev_b32_e32 v52, 2, v52
	ds_bpermute_b32 v53, v52, v3
	ds_bpermute_b32 v52, v52, v24
	v_lshlrev_b32_e32 v54, 16, v48
	v_and_b32_e32 v48, 0xffff0000, v48
	v_mov_b32_e32 v55, v2
	s_waitcnt lgkmcnt(1)
	v_sub_f32_e32 v54, v54, v53
	v_sub_f32_e32 v48, v48, v53
	s_waitcnt lgkmcnt(0)
	v_mul_f32_e32 v54, v54, v52
	v_mul_f32_e32 v48, v48, v52
	v_fma_f32 v54, v32, v54, v40
	v_fma_f32 v48, v33, v48, v41
	v_cvt_pk_bf16_f32 v48, v54, v48
	v_lshlrev_b32_e32 v54, 16, v49
	v_and_b32_e32 v49, 0xffff0000, v49
	v_sub_f32_e32 v54, v54, v53
	v_sub_f32_e32 v49, v49, v53
	v_mul_f32_e32 v54, v54, v52
	v_mul_f32_e32 v49, v49, v52
	v_fma_f32 v54, v34, v54, v42
	v_fma_f32 v49, v35, v49, v43
	v_cvt_pk_bf16_f32 v49, v54, v49
	v_lshlrev_b32_e32 v54, 16, v50
	v_and_b32_e32 v50, 0xffff0000, v50
	v_sub_f32_e32 v54, v54, v53
	v_sub_f32_e32 v50, v50, v53
	v_mul_f32_e32 v54, v54, v52
	v_mul_f32_e32 v50, v50, v52
	v_fma_f32 v54, v20, v54, v28
	v_fma_f32 v50, v21, v50, v29
	v_cvt_pk_bf16_f32 v50, v54, v50
	v_lshlrev_b32_e32 v54, 16, v51
	v_and_b32_e32 v51, 0xffff0000, v51
	v_sub_f32_e32 v51, v51, v53
	v_sub_f32_e32 v54, v54, v53
	v_mul_f32_e32 v51, v51, v52
	v_mul_f32_e32 v54, v54, v52
	v_fma_f32 v51, v23, v51, v31
	v_add_u32_e32 v52, 0x2640, v135
	v_fma_f32 v54, v22, v54, v30
	v_cvt_pk_bf16_f32 v51, v54, v51
	ds_write2_b64 v52, v[48:49], v[50:51] offset1:1
	v_or_b32_e32 v48, v25, v123
	v_lshlrev_b32_e32 v48, 2, v48
	ds_bpermute_b32 v49, v48, v3
	ds_bpermute_b32 v48, v48, v24
	v_lshlrev_b32_e32 v50, 16, v44
	v_and_b32_e32 v44, 0xffff0000, v44
	v_mov_b32_e32 v51, v2
	s_waitcnt lgkmcnt(1)
	v_sub_f32_e32 v50, v50, v49
	v_sub_f32_e32 v44, v44, v49
	s_waitcnt lgkmcnt(0)
	v_mul_f32_e32 v50, v50, v48
	v_mul_f32_e32 v44, v44, v48
	v_fma_f32 v50, v32, v50, v40
	v_fma_f32 v44, v33, v44, v41
	v_cvt_pk_bf16_f32 v44, v50, v44
	v_lshlrev_b32_e32 v50, 16, v45
	v_and_b32_e32 v45, 0xffff0000, v45
	v_sub_f32_e32 v50, v50, v49
	v_sub_f32_e32 v45, v45, v49
	v_mul_f32_e32 v50, v50, v48
	v_mul_f32_e32 v45, v45, v48
	v_fma_f32 v50, v34, v50, v42
	v_fma_f32 v45, v35, v45, v43
	v_cvt_pk_bf16_f32 v45, v50, v45
	v_lshlrev_b32_e32 v50, 16, v46
	v_and_b32_e32 v46, 0xffff0000, v46
	v_sub_f32_e32 v50, v50, v49
	v_sub_f32_e32 v46, v46, v49
	v_mul_f32_e32 v50, v50, v48
	v_mul_f32_e32 v46, v46, v48
	v_fma_f32 v50, v20, v50, v28
	v_fma_f32 v46, v21, v46, v29
	v_cvt_pk_bf16_f32 v46, v50, v46
	v_lshlrev_b32_e32 v50, 16, v47
	v_and_b32_e32 v47, 0xffff0000, v47
	v_sub_f32_e32 v47, v47, v49
	v_sub_f32_e32 v50, v50, v49
	v_mul_f32_e32 v47, v47, v48
	v_mul_f32_e32 v50, v50, v48
	v_fma_f32 v47, v23, v47, v31
	v_add_u32_e32 v48, 0x2a80, v135
	v_fma_f32 v50, v22, v50, v30
	v_cvt_pk_bf16_f32 v47, v50, v47
	ds_write2_b64 v48, v[44:45], v[46:47] offset1:1
	v_or_b32_e32 v44, v25, v124
	v_lshlrev_b32_e32 v44, 2, v44
	ds_bpermute_b32 v45, v44, v3
	ds_bpermute_b32 v44, v44, v24
	v_lshlrev_b32_e32 v46, 16, v36
	v_and_b32_e32 v36, 0xffff0000, v36
	v_mov_b32_e32 v47, v2
	s_waitcnt lgkmcnt(1)
	v_sub_f32_e32 v46, v46, v45
	v_sub_f32_e32 v36, v36, v45
	s_waitcnt lgkmcnt(0)
	v_mul_f32_e32 v46, v46, v44
	v_mul_f32_e32 v36, v36, v44
	v_fma_f32 v46, v32, v46, v40
	v_fma_f32 v36, v33, v36, v41
	v_cvt_pk_bf16_f32 v36, v46, v36
	v_lshlrev_b32_e32 v46, 16, v37
	v_and_b32_e32 v37, 0xffff0000, v37
	v_sub_f32_e32 v46, v46, v45
	v_sub_f32_e32 v37, v37, v45
	v_mul_f32_e32 v46, v46, v44
	v_mul_f32_e32 v37, v37, v44
	v_fma_f32 v46, v34, v46, v42
	v_fma_f32 v37, v35, v37, v43
	v_cvt_pk_bf16_f32 v37, v46, v37
	v_lshlrev_b32_e32 v46, 16, v38
	v_and_b32_e32 v38, 0xffff0000, v38
	v_sub_f32_e32 v46, v46, v45
	v_sub_f32_e32 v38, v38, v45
	v_mul_f32_e32 v46, v46, v44
	v_mul_f32_e32 v38, v38, v44
	v_fma_f32 v46, v20, v46, v28
	v_fma_f32 v38, v21, v38, v29
	v_cvt_pk_bf16_f32 v38, v46, v38
	v_lshlrev_b32_e32 v46, 16, v39
	v_and_b32_e32 v39, 0xffff0000, v39
	v_sub_f32_e32 v39, v39, v45
	v_sub_f32_e32 v46, v46, v45
	v_mul_f32_e32 v39, v39, v44
	v_mul_f32_e32 v46, v46, v44
	v_fma_f32 v39, v23, v39, v31
	v_add_u32_e32 v44, 0x2ec0, v135
	v_fma_f32 v46, v22, v46, v30
	v_cvt_pk_bf16_f32 v39, v46, v39
	ds_write2_b64 v44, v[36:37], v[38:39] offset1:1
	v_or_b32_e32 v36, v25, v125
	v_lshlrev_b32_e32 v36, 2, v36
	ds_bpermute_b32 v37, v36, v3
	ds_bpermute_b32 v36, v36, v24
	v_lshlrev_b32_e32 v38, 16, v16
	v_and_b32_e32 v16, 0xffff0000, v16
	v_mov_b32_e32 v39, v2
	s_waitcnt lgkmcnt(1)
	v_sub_f32_e32 v38, v38, v37
	v_sub_f32_e32 v16, v16, v37
	s_waitcnt lgkmcnt(0)
	v_mul_f32_e32 v38, v38, v36
	v_mul_f32_e32 v16, v16, v36
	v_fma_f32 v38, v32, v38, v40
	v_fma_f32 v16, v33, v16, v41
	v_cvt_pk_bf16_f32 v16, v38, v16
	v_lshlrev_b32_e32 v38, 16, v17
	v_and_b32_e32 v17, 0xffff0000, v17
	v_sub_f32_e32 v38, v38, v37
	v_sub_f32_e32 v17, v17, v37
	v_mul_f32_e32 v38, v38, v36
	v_mul_f32_e32 v17, v17, v36
	v_fma_f32 v38, v34, v38, v42
	v_fma_f32 v17, v35, v17, v43
	v_cvt_pk_bf16_f32 v17, v38, v17
	v_lshlrev_b32_e32 v38, 16, v18
	v_and_b32_e32 v18, 0xffff0000, v18
	v_sub_f32_e32 v38, v38, v37
	v_sub_f32_e32 v18, v18, v37
	v_mul_f32_e32 v38, v38, v36
	v_mul_f32_e32 v18, v18, v36
	v_fma_f32 v38, v20, v38, v28
	v_fma_f32 v18, v21, v18, v29
	v_cvt_pk_bf16_f32 v18, v38, v18
	v_lshlrev_b32_e32 v38, 16, v19
	v_and_b32_e32 v19, 0xffff0000, v19
	v_sub_f32_e32 v19, v19, v37
	v_sub_f32_e32 v38, v38, v37
	v_mul_f32_e32 v19, v19, v36
	v_mul_f32_e32 v38, v38, v36
	v_fma_f32 v19, v23, v19, v31
	v_add_u32_e32 v36, 0x3300, v135
	v_fma_f32 v38, v22, v38, v30
	v_cvt_pk_bf16_f32 v19, v38, v19
	ds_write2_b64 v36, v[16:17], v[18:19] offset1:1
	v_or_b32_e32 v16, v25, v126
	v_lshlrev_b32_e32 v16, 2, v16
	ds_bpermute_b32 v17, v16, v3
	ds_bpermute_b32 v16, v16, v24
	v_lshlrev_b32_e32 v18, 16, v12
	v_and_b32_e32 v12, 0xffff0000, v12
	v_mov_b32_e32 v19, v2
	s_waitcnt lgkmcnt(1)
	v_sub_f32_e32 v18, v18, v17
	v_sub_f32_e32 v12, v12, v17
	s_waitcnt lgkmcnt(0)
	v_mul_f32_e32 v18, v18, v16
	v_mul_f32_e32 v12, v12, v16
	v_fma_f32 v18, v32, v18, v40
	v_fma_f32 v12, v33, v12, v41
	v_cvt_pk_bf16_f32 v12, v18, v12
	v_lshlrev_b32_e32 v18, 16, v13
	v_and_b32_e32 v13, 0xffff0000, v13
	v_sub_f32_e32 v18, v18, v17
	v_sub_f32_e32 v13, v13, v17
	v_mul_f32_e32 v18, v18, v16
	v_mul_f32_e32 v13, v13, v16
	v_fma_f32 v18, v34, v18, v42
	v_fma_f32 v13, v35, v13, v43
	v_cvt_pk_bf16_f32 v13, v18, v13
	v_lshlrev_b32_e32 v18, 16, v14
	v_and_b32_e32 v14, 0xffff0000, v14
	v_sub_f32_e32 v18, v18, v17
	v_sub_f32_e32 v14, v14, v17
	v_mul_f32_e32 v18, v18, v16
	v_mul_f32_e32 v14, v14, v16
	v_fma_f32 v18, v20, v18, v28
	v_fma_f32 v14, v21, v14, v29
	v_cvt_pk_bf16_f32 v14, v18, v14
	v_lshlrev_b32_e32 v18, 16, v15
	v_and_b32_e32 v15, 0xffff0000, v15
	v_sub_f32_e32 v15, v15, v17
	v_sub_f32_e32 v18, v18, v17
	v_mul_f32_e32 v15, v15, v16
	v_mul_f32_e32 v18, v18, v16
	v_fma_f32 v15, v23, v15, v31
	v_add_u32_e32 v16, 0x3740, v135
	v_fma_f32 v18, v22, v18, v30
	v_cvt_pk_bf16_f32 v15, v18, v15
	ds_write2_b64 v16, v[12:13], v[14:15] offset1:1
	v_or_b32_e32 v12, v25, v127
	v_lshlrev_b32_e32 v12, 2, v12
	ds_bpermute_b32 v13, v12, v3
	ds_bpermute_b32 v12, v12, v24
	v_lshlrev_b32_e32 v14, 16, v8
	v_and_b32_e32 v8, 0xffff0000, v8
	v_mov_b32_e32 v18, v2
	s_waitcnt lgkmcnt(1)
	v_sub_f32_e32 v14, v14, v13
	v_sub_f32_e32 v8, v8, v13
	s_waitcnt lgkmcnt(0)
	v_mul_f32_e32 v14, v14, v12
	v_mul_f32_e32 v8, v8, v12
	v_fma_f32 v14, v32, v14, v40
	v_fma_f32 v8, v33, v8, v41
	v_cvt_pk_bf16_f32 v8, v14, v8
	v_lshlrev_b32_e32 v14, 16, v9
	v_and_b32_e32 v9, 0xffff0000, v9
	v_sub_f32_e32 v14, v14, v13
	v_sub_f32_e32 v9, v9, v13
	v_mul_f32_e32 v14, v14, v12
	v_mul_f32_e32 v9, v9, v12
	v_fma_f32 v14, v34, v14, v42
	v_fma_f32 v9, v35, v9, v43
	v_cvt_pk_bf16_f32 v9, v14, v9
	v_lshlrev_b32_e32 v14, 16, v10
	v_and_b32_e32 v10, 0xffff0000, v10
	v_sub_f32_e32 v14, v14, v13
	v_sub_f32_e32 v10, v10, v13
	v_mul_f32_e32 v14, v14, v12
	v_mul_f32_e32 v10, v10, v12
	v_fma_f32 v14, v20, v14, v28
	v_fma_f32 v10, v21, v10, v29
	v_cvt_pk_bf16_f32 v10, v14, v10
	v_lshlrev_b32_e32 v14, 16, v11
	v_and_b32_e32 v11, 0xffff0000, v11
	v_sub_f32_e32 v11, v11, v13
	v_sub_f32_e32 v14, v14, v13
	v_mul_f32_e32 v11, v11, v12
	v_mul_f32_e32 v14, v14, v12
	v_fma_f32 v11, v23, v11, v31
	v_add_u32_e32 v12, 0x3b80, v135
	v_fma_f32 v14, v22, v14, v30
	v_cvt_pk_bf16_f32 v11, v14, v11
	ds_write2_b64 v12, v[8:9], v[10:11] offset1:1
	v_or_b32_e32 v8, v25, v128
	v_lshlrev_b32_e32 v8, 2, v8
	ds_bpermute_b32 v3, v8, v3
	ds_bpermute_b32 v8, v8, v24
	v_lshlrev_b32_e32 v9, 16, v4
	v_and_b32_e32 v4, 0xffff0000, v4
	v_mov_b32_e32 v10, v2
	s_waitcnt lgkmcnt(1)
	v_sub_f32_e32 v9, v9, v3
	v_sub_f32_e32 v4, v4, v3
	s_waitcnt lgkmcnt(0)
	v_mul_f32_e32 v9, v9, v8
	v_mul_f32_e32 v4, v4, v8
	v_fma_f32 v9, v32, v9, v40
	v_fma_f32 v4, v33, v4, v41
	v_cvt_pk_bf16_f32 v4, v9, v4
	v_lshlrev_b32_e32 v9, 16, v5
	v_sub_f32_e32 v9, v9, v3
	v_and_b32_e32 v5, 0xffff0000, v5
	v_mul_f32_e32 v9, v9, v8
	v_sub_f32_e32 v5, v5, v3
	v_fma_f32 v9, v34, v9, v42
	v_mul_f32_e32 v5, v5, v8
	v_fmac_f32_e32 v43, v35, v5
	v_cvt_pk_bf16_f32 v5, v9, v43
	v_lshlrev_b32_e32 v9, 16, v6
	v_and_b32_e32 v6, 0xffff0000, v6
	v_sub_f32_e32 v9, v9, v3
	v_sub_f32_e32 v6, v6, v3
	v_mul_f32_e32 v9, v9, v8
	v_mul_f32_e32 v6, v6, v8
	v_fma_f32 v9, v20, v9, v28
	v_fma_f32 v6, v21, v6, v29
	v_cvt_pk_bf16_f32 v6, v9, v6
	v_lshlrev_b32_e32 v9, 16, v7
	v_and_b32_e32 v7, 0xffff0000, v7
	v_sub_f32_e32 v9, v9, v3
	v_sub_f32_e32 v3, v7, v3
	v_mul_f32_e32 v3, v3, v8
	v_mul_f32_e32 v9, v9, v8
	v_fmac_f32_e32 v31, v23, v3
	v_add_u32_e32 v3, 0x3fc0, v135
	v_fma_f32 v9, v22, v9, v30
	v_cvt_pk_bf16_f32 v7, v9, v31
	ds_write2_b64 v3, v[4:5], v[6:7] offset1:1
	s_waitcnt lgkmcnt(0)
	v_mov_b32_e32 v3, v2
	v_mov_b32_e32 v4, v2
	v_mov_b32_e32 v5, v2
	v_mov_b32_e32 v6, v2
	v_mov_b32_e32 v7, v2
	v_mov_b32_e32 v8, v2
	v_mov_b32_e32 v9, v2
	v_mov_b32_e32 v11, v2
	v_mov_b32_e32 v12, v2
	v_mov_b32_e32 v13, v2
	v_mov_b32_e32 v20, v2
	v_mov_b32_e32 v21, v2
	v_mov_b32_e32 v14, v2
	v_mov_b32_e32 v15, v2
	v_mov_b32_e32 v16, v2
	v_mov_b32_e32 v17, v2
	v_mov_b32_e32 v22, v2
	v_mov_b32_e32 v23, v2
	v_mov_b32_e32 v24, v2
	v_mov_b32_e32 v25, v2
	v_mov_b32_e32 v28, v2
	v_mov_b32_e32 v29, v2
	v_mov_b32_e32 v30, v2
	v_mov_b32_e32 v31, v2
	v_mov_b32_e32 v36, v2
	v_mov_b32_e32 v37, v2
	v_mov_b32_e32 v38, v2
	v_mov_b32_e32 v32, v2
	v_mov_b32_e32 v33, v2
	v_mov_b32_e32 v34, v2
	v_mov_b32_e32 v35, v2
	v_mov_b32_e32 v40, v2
	v_mov_b32_e32 v41, v2
	v_mov_b32_e32 v42, v2
	v_mov_b32_e32 v43, v2
	v_mov_b32_e32 v44, v2
	v_mov_b32_e32 v45, v2
	v_mov_b32_e32 v46, v2
	v_mov_b32_e32 v48, v2
	v_mov_b32_e32 v49, v2
	v_mov_b32_e32 v50, v2
	v_mov_b32_e32 v52, v2
	v_mov_b32_e32 v53, v2
	v_mov_b32_e32 v54, v2
	v_mov_b32_e32 v56, v2
	v_mov_b32_e32 v57, v2
	v_mov_b32_e32 v58, v2
	v_mov_b32_e32 v60, v2
	v_mov_b32_e32 v61, v2
	v_mov_b32_e32 v62, v2
